# SwiGLU epilogue fully regenerated; per-row 1/rms kept in spare VGPRs and reused while consecutive tiles share the row block (skips 8 loads + conversions on a hit)
# baseline (speedup 1.0000x reference)
.LBB0_102:
	s_mov_b32 s100, -1
	v_writelane_b32 v255, s100, 48
	s_mul_i32 s2, s6, 0x3700000
	s_add_u32 s2, s2, 0x100000
	v_writelane_b32 v255, s2, 10
	s_addc_u32 s2, 0, 0
	v_writelane_b32 v255, s2, 11
	s_mov_b64 s[2:3], s[78:79]
	s_load_dwordx2 s[4:5], s[2:3], 0xf0
	s_mov_b32 s34, s76
	s_mov_b32 s36, s97
	v_mov_b32_e32 v1, v218
	v_writelane_b32 v255, s6, 12
	s_lshl_b32 s2, s6, 17
	s_mov_b32 s3, s81
	v_writelane_b32 v255, s2, 13
	s_ashr_i32 s35, s34, 31
	s_ashr_i32 s37, s36, 31
	v_mov_b32_e32 v1, v218
	v_writelane_b32 v255, s3, 14
	s_cmpk_lt_i32 s36, 0xb00
	s_nop 0
	v_readfirstlane_b32 s3, v1
	s_cbranch_scc0 .LBB0_118
	v_lshlrev_b32_e32 v2, 4, v1
	v_add_u32_e32 v3, 0x2000, v2
	v_ashrrev_i32_e32 v4, 31, v3
	v_lshrrev_b32_e32 v4, 22, v4
	v_add_u32_e32 v4, v3, v4
	s_waitcnt vmcnt(19)
	v_ashrrev_i32_e32 v10, 10, v4
	v_mul_i32_i24_e32 v4, 0x400, v10
	v_sub_u32_e32 v3, v3, v4
	v_lshrrev_b32_e32 v4, 4, v3
	s_waitcnt lgkmcnt(0)
	s_add_u32 s38, s4, 0x9700000
	v_bitop3_b32 v3, v4, v3, 32 bitop3:0x6c
	s_addc_u32 s39, s5, 0
	v_readlane_b32 s2, v255, 10
	v_ashrrev_i32_e32 v4, 31, v3
	s_add_u32 s40, s4, s2
	v_readlane_b32 s2, v255, 11
	v_lshrrev_b32_e32 v4, 26, v4
	s_addc_u32 s41, s5, s2
	v_add_u32_e32 v4, v3, v4
	v_lshlrev_b32_e32 v5, 3, v10
	s_ashr_i32 s2, s36, 31
	v_ashrrev_i32_e32 v11, 6, v4
	v_and_b32_e32 v5, -16, v5
	s_lshr_b32 s2, s2, 29
	v_add_u32_e32 v5, v11, v5
	s_add_i32 s2, s36, s2
	s_ashr_i32 s14, s3, 6
	v_and_b32_e32 v6, 3, v11
	v_lshrrev_b32_e32 v7, 2, v5
	v_lshlrev_b32_e32 v8, 1, v5
	v_and_b32_e32 v4, 0xc0, v4
	s_ashr_i32 s6, s2, 3
	s_and_b32 s2, s2, -8
	s_ashr_i32 s15, s3, 8
	s_lshl_b32 s42, s14, 10
	v_and_or_b32 v6, v5, s69, v6
	v_and_b32_e32 v7, 4, v7
	v_and_b32_e32 v8, 24, v8
	v_sub_u32_e32 v3, v3, v4
	s_sub_i32 s2, s36, s2
	v_or3_b32 v6, v6, v7, v8
	v_lshlrev_b32_e32 v7, 5, v10
	v_ashrrev_i16_sdwa v3, v253, sext(v3) dst_sel:DWORD dst_unused:UNUSED_PAD src0_sel:DWORD src1_sel:BYTE_0
	s_cmp_lt_i32 s2, 0
	v_and_b32_e32 v7, 32, v7
	v_bfe_i32 v12, v3, 0, 16
	s_cselect_b32 s7, s70, 0x160
	v_add_lshl_u32 v3, v7, v12, 1
	s_mul_i32 s2, s2, s7
	v_lshl_add_u32 v130, v6, 11, v3
	v_lshl_add_u32 v132, v5, 11, v3
	v_bfe_i32 v3, v1, 27, 1
	s_add_i32 s2, s2, s6
	v_lshrrev_b32_e32 v3, 22, v3
	s_mul_hi_i32 s6, s2, 0x2e8ba2e9
	v_add_u32_e32 v3, v2, v3
	s_lshr_b32 s7, s6, 31
	s_ashr_i32 s6, s6, 4
	v_and_b32_e32 v3, 0xfffffc00, v3
	s_add_i32 s6, s6, s7
	v_sub_u32_e32 v2, v2, v3
	s_lshl_b32 s7, s6, 2
	s_mulk_i32 s6, 0x58
	v_lshrrev_b32_e32 v3, 4, v2
	v_ashrrev_i32_e32 v4, 31, v1
	s_sub_i32 s6, s2, s6
	v_bitop3_b32 v2, v3, v2, 32 bitop3:0x6c
	v_lshrrev_b32_e32 v4, 26, v4
	s_bfe_i32 s2, s6, 0x80000
	v_ashrrev_i32_e32 v3, 31, v2
	v_add_u32_e32 v4, v1, v4
	s_bfe_u32 s2, s2, 0x2000d
	v_lshrrev_b32_e32 v3, 26, v3
	v_ashrrev_i32_e32 v14, 6, v4
	s_add_i32 s8, s6, s2
	v_add_u32_e32 v3, v2, v3
	v_lshlrev_b32_e32 v4, 3, v14
	s_bfe_i32 s2, s8, 0x80000
	s_and_b32 s8, s8, 0xfc
	v_ashrrev_i32_e32 v13, 6, v3
	v_and_b32_e32 v4, -16, v4
	s_sub_i32 s6, s6, s8
	v_add_u32_e32 v4, v13, v4
	s_sext_i32_i16 s2, s2
	s_sext_i32_i8 s6, s6
	v_and_b32_e32 v5, 3, v13
	v_lshrrev_b32_e32 v6, 2, v4
	v_lshlrev_b32_e32 v7, 1, v4
	v_and_b32_e32 v3, 0xc0, v3
	s_lshr_b32 s2, s2, 2
	s_add_i32 s24, s7, s6
	v_and_or_b32 v5, v4, s69, v5
	v_and_b32_e32 v6, 4, v6
	v_and_b32_e32 v7, 24, v7
	v_sub_u32_e32 v2, v2, v3
	s_ashr_i32 s25, s24, 31
	s_bfe_i64 s[8:9], s[2:3], 0x100000
	v_or3_b32 v5, v5, v6, v7
	v_lshlrev_b32_e32 v6, 5, v14
	v_ashrrev_i16_sdwa v2, v253, sext(v2) dst_sel:DWORD dst_unused:UNUSED_PAD src0_sel:DWORD src1_sel:BYTE_0
	s_lshl_b64 s[6:7], s[24:25], 19
	s_lshl_b64 s[8:9], s[8:9], 19
	v_and_b32_e32 v6, 32, v6
	v_bfe_i32 v15, v2, 0, 16
	s_add_u32 s28, s40, s8
	v_add_lshl_u32 v2, v6, v15, 1
	s_addc_u32 s29, s41, s9
	s_add_i32 s43, s42, 0
	v_lshl_add_u32 v134, v5, 11, v2
	s_add_i32 m0, s43, 0x10000
	v_lshl_add_u32 v136, v4, 11, v2
	global_load_lds_dwordx4 v134, s[28:29]
	s_add_i32 m0, s43, 0x12000
	s_add_u32 s8, s28, 0x40000
	global_load_lds_dwordx4 v130, s[28:29]
	s_addc_u32 s9, s29, 0
	s_add_i32 m0, s43, 0x14000
	v_mov_b32_e32 v135, v0
	global_load_lds_dwordx4 v134, s[8:9]
	s_add_i32 m0, s43, 0x16000
	s_add_u32 s26, s38, s6
	s_addc_u32 s27, s39, s7
	s_add_i32 s44, s43, 0x2000
	global_load_lds_dwordx4 v130, s[8:9]
	s_mov_b32 m0, s43
	s_add_u32 s6, s26, 0x40000
	global_load_lds_dwordx4 v136, s[26:27]
	s_mov_b32 m0, s44
	s_addc_u32 s7, s27, 0
	s_add_i32 s45, s43, 0x4000
	global_load_lds_dwordx4 v132, s[26:27]
	s_mov_b32 m0, s45
	s_add_i32 s46, s43, 0x6000
	global_load_lds_dwordx4 v136, s[6:7]
	s_mov_b32 m0, s46
	v_mov_b32_e32 v131, v0
	global_load_lds_dwordx4 v132, s[6:7]
	v_mov_b32_e32 v137, v0
	v_mov_b32_e32 v133, v0
	s_cmp_eq_u32 s15, 1
	v_lshl_add_u64 v[8:9], s[28:29], 0, v[134:135]
	v_lshl_add_u64 v[6:7], s[28:29], 0, v[130:131]
	v_lshl_add_u64 v[2:3], s[26:27], 0, v[136:137]
	s_cselect_b64 s[6:7], -1, 0
	s_cmp_lg_u32 s15, 1
	v_lshl_add_u64 v[4:5], s[26:27], 0, v[132:133]
	s_cbranch_scc1 .LBB0_105
	s_barrier

.LBB0_114:
	v_mov_b32_e32 v143, v218
	s_lshl_b32 s17, s24, 8
	s_add_i32 s17, s17, s47
	v_and_or_b32 v142, v143, 15, s17
	s_lshl_b32 s17, s25, 7
	v_lshrrev_b32_e32 v143, 1, v143
	v_and_or_b32 v143, v143, 24, s17
	v_or_b32_e32 v148, s48, v143
	v_ashrrev_i32_e32 v143, 31, v142
	v_lshl_add_u64 v[144:145], v[142:143], 3, s[10:11]
	v_ashrrev_i32_e32 v149, 31, v148
	v_lshlrev_b64 v[176:177], 1, v[148:149]
	v_mov_b64_e32 v[174:175], s[8:9]
	v_readlane_b32 s100, v255, 48
	s_nop 3
	s_cmp_eq_u32 s100, s24
	s_cbranch_scc1 .Lrs_hit_a
	global_load_dwordx2 v[146:147], v[144:145], off
	global_load_dwordx2 v[158:159], v[144:145], off offset:128
	global_load_dwordx2 v[160:161], v[144:145], off offset:256
	global_load_dwordx2 v[162:163], v[144:145], off offset:384
	global_load_dwordx2 v[164:165], v[144:145], off offset:1024
	global_load_dwordx2 v[166:167], v[144:145], off offset:1152
	global_load_dwordx2 v[168:169], v[144:145], off offset:1280
	global_load_dwordx2 v[170:171], v[144:145], off offset:1408
	v_writelane_b32 v255, s24, 48
	s_waitcnt vmcnt(0)
	v_ffbh_u32_e32 v180, v147
	v_min_u32_e32 v180, 32, v180
	v_lshlrev_b64 v[178:179], v180, v[146:147]
	v_min_u32_e32 v178, 1, v178
	v_or_b32_e32 v178, v179, v178
	v_cvt_f32_u32_e32 v178, v178
	v_sub_u32_e32 v179, 32, v180
	v_ldexp_f32 v178, v178, v179
	v_fmamk_f32 v178, v178, 0x31800000, v219
	v_rsq_f32_e32 v238, v178
	v_ffbh_u32_e32 v180, v159
	v_min_u32_e32 v180, 32, v180
	v_lshlrev_b64 v[178:179], v180, v[158:159]
	v_min_u32_e32 v178, 1, v178
	v_or_b32_e32 v178, v179, v178
	v_cvt_f32_u32_e32 v178, v178
	v_sub_u32_e32 v179, 32, v180
	v_ldexp_f32 v178, v178, v179
	v_fmamk_f32 v178, v178, 0x31800000, v219
	v_rsq_f32_e32 v240, v178
	v_ffbh_u32_e32 v180, v161
	v_min_u32_e32 v180, 32, v180
	v_lshlrev_b64 v[178:179], v180, v[160:161]
	v_min_u32_e32 v178, 1, v178
	v_or_b32_e32 v178, v179, v178
	v_cvt_f32_u32_e32 v178, v178
	v_sub_u32_e32 v179, 32, v180
	v_ldexp_f32 v178, v178, v179
	v_fmamk_f32 v178, v178, 0x31800000, v219
	v_rsq_f32_e32 v242, v178
	v_ffbh_u32_e32 v180, v163
	v_min_u32_e32 v180, 32, v180
	v_lshlrev_b64 v[178:179], v180, v[162:163]
	v_min_u32_e32 v178, 1, v178
	v_or_b32_e32 v178, v179, v178
	v_cvt_f32_u32_e32 v178, v178
	v_sub_u32_e32 v179, 32, v180
	v_ldexp_f32 v178, v178, v179
	v_fmamk_f32 v178, v178, 0x31800000, v219
	v_rsq_f32_e32 v244, v178
	v_ffbh_u32_e32 v180, v165
	v_min_u32_e32 v180, 32, v180
	v_lshlrev_b64 v[178:179], v180, v[164:165]
	v_min_u32_e32 v178, 1, v178
	v_or_b32_e32 v178, v179, v178
	v_cvt_f32_u32_e32 v178, v178
	v_sub_u32_e32 v179, 32, v180
	v_ldexp_f32 v178, v178, v179
	v_fmamk_f32 v178, v178, 0x31800000, v219
	v_rsq_f32_e32 v246, v178
	v_ffbh_u32_e32 v180, v167
	v_min_u32_e32 v180, 32, v180
	v_lshlrev_b64 v[178:179], v180, v[166:167]
	v_min_u32_e32 v178, 1, v178
	v_or_b32_e32 v178, v179, v178
	v_cvt_f32_u32_e32 v178, v178
	v_sub_u32_e32 v179, 32, v180
	v_ldexp_f32 v178, v178, v179
	v_fmamk_f32 v178, v178, 0x31800000, v219
	v_rsq_f32_e32 v248, v178
	v_ffbh_u32_e32 v180, v169
	v_min_u32_e32 v180, 32, v180
	v_lshlrev_b64 v[178:179], v180, v[168:169]
	v_min_u32_e32 v178, 1, v178
	v_or_b32_e32 v178, v179, v178
	v_cvt_f32_u32_e32 v178, v178
	v_sub_u32_e32 v179, 32, v180
	v_ldexp_f32 v178, v178, v179
	v_fmamk_f32 v178, v178, 0x31800000, v219
	v_rsq_f32_e32 v250, v178
	v_ffbh_u32_e32 v180, v171
	v_min_u32_e32 v180, 32, v180
	v_lshlrev_b64 v[178:179], v180, v[170:171]
	v_min_u32_e32 v178, 1, v178
	v_or_b32_e32 v178, v179, v178
	v_cvt_f32_u32_e32 v178, v178
	v_sub_u32_e32 v179, 32, v180
	v_ldexp_f32 v178, v178, v179
	v_fmamk_f32 v178, v178, 0x31800000, v219
	v_rsq_f32_e32 v252, v178
.Lrs_hit_a:
	v_mov_b32_e32 v192, 0xbfb8aa3b
	v_mad_i64_i32 v[182:183], s[24:25], v142, s83, v[174:175]
	v_pk_mul_f32 v[126:127], v[126:127], v[238:239] op_sel_hi:[1,0]
	v_pk_mul_f32 v[128:129], v[128:129], v[238:239] op_sel_hi:[1,0]
	v_pk_mul_f32 v[122:123], v[122:123], v[238:239] op_sel_hi:[1,0]
	v_pk_mul_f32 v[124:125], v[124:125], v[238:239] op_sel_hi:[1,0]
	v_pk_mul_f32 v[118:119], v[118:119], v[238:239] op_sel_hi:[1,0]
	v_pk_mul_f32 v[120:121], v[120:121], v[238:239] op_sel_hi:[1,0]
	v_pk_mul_f32 v[114:115], v[114:115], v[238:239] op_sel_hi:[1,0]
	v_pk_mul_f32 v[116:117], v[116:117], v[238:239] op_sel_hi:[1,0]
	v_pk_mul_f32 v[188:189], v[126:127], v[192:193] op_sel_hi:[1,0]
	v_pk_mul_f32 v[190:191], v[128:129], v[192:193] op_sel_hi:[1,0]
	v_exp_f32_e32 v188, v188
	v_exp_f32_e32 v189, v189
	v_exp_f32_e32 v190, v190
	v_exp_f32_e32 v191, v191
	v_pk_add_f32 v[188:189], v[188:189], 1.0 op_sel_hi:[1,0]
	v_pk_add_f32 v[190:191], v[190:191], 1.0 op_sel_hi:[1,0]
	v_rcp_f32_e32 v188, v188
	v_rcp_f32_e32 v189, v189
	v_rcp_f32_e32 v190, v190
	v_rcp_f32_e32 v191, v191
	v_pk_mul_f32 v[126:127], v[126:127], v[188:189]
	v_pk_mul_f32 v[128:129], v[128:129], v[190:191]
	v_pk_mul_f32 v[118:119], v[118:119], v[126:127]
	v_pk_mul_f32 v[120:121], v[120:121], v[128:129]
	v_cvt_pk_bf16_f32 v184, v118, v119
	v_cvt_pk_bf16_f32 v185, v120, v121
	v_pk_mul_f32 v[188:189], v[122:123], v[192:193] op_sel_hi:[1,0]
	v_pk_mul_f32 v[190:191], v[124:125], v[192:193] op_sel_hi:[1,0]
	v_exp_f32_e32 v188, v188
	v_exp_f32_e32 v189, v189
	v_exp_f32_e32 v190, v190
	v_exp_f32_e32 v191, v191
	v_pk_add_f32 v[188:189], v[188:189], 1.0 op_sel_hi:[1,0]
	v_pk_add_f32 v[190:191], v[190:191], 1.0 op_sel_hi:[1,0]
	v_rcp_f32_e32 v188, v188
	v_rcp_f32_e32 v189, v189
	v_rcp_f32_e32 v190, v190
	v_rcp_f32_e32 v191, v191
	v_pk_mul_f32 v[122:123], v[122:123], v[188:189]
	v_pk_mul_f32 v[124:125], v[124:125], v[190:191]
	v_pk_mul_f32 v[114:115], v[114:115], v[122:123]
	v_pk_mul_f32 v[116:117], v[116:117], v[124:125]
	v_cvt_pk_bf16_f32 v186, v114, v115
	v_cvt_pk_bf16_f32 v187, v116, v117
	v_lshl_add_u64 v[182:183], v[182:183], 0, v[176:177]
	global_store_dwordx4 v[182:183], v[184:187], off
	v_or_b32_e32 v181, 16, v142
	v_mad_i64_i32 v[182:183], s[24:25], v181, s83, v[174:175]
	v_pk_mul_f32 v[110:111], v[110:111], v[240:241] op_sel_hi:[1,0]
	v_pk_mul_f32 v[112:113], v[112:113], v[240:241] op_sel_hi:[1,0]
	v_pk_mul_f32 v[106:107], v[106:107], v[240:241] op_sel_hi:[1,0]
	v_pk_mul_f32 v[108:109], v[108:109], v[240:241] op_sel_hi:[1,0]
	v_pk_mul_f32 v[102:103], v[102:103], v[240:241] op_sel_hi:[1,0]
	v_pk_mul_f32 v[104:105], v[104:105], v[240:241] op_sel_hi:[1,0]
	v_pk_mul_f32 v[98:99], v[98:99], v[240:241] op_sel_hi:[1,0]
	v_pk_mul_f32 v[100:101], v[100:101], v[240:241] op_sel_hi:[1,0]
	v_pk_mul_f32 v[188:189], v[110:111], v[192:193] op_sel_hi:[1,0]
	v_pk_mul_f32 v[190:191], v[112:113], v[192:193] op_sel_hi:[1,0]
	v_exp_f32_e32 v188, v188
	v_exp_f32_e32 v189, v189
	v_exp_f32_e32 v190, v190
	v_exp_f32_e32 v191, v191
	v_pk_add_f32 v[188:189], v[188:189], 1.0 op_sel_hi:[1,0]
	v_pk_add_f32 v[190:191], v[190:191], 1.0 op_sel_hi:[1,0]
	v_rcp_f32_e32 v188, v188
	v_rcp_f32_e32 v189, v189
	v_rcp_f32_e32 v190, v190
	v_rcp_f32_e32 v191, v191
	v_pk_mul_f32 v[110:111], v[110:111], v[188:189]
	v_pk_mul_f32 v[112:113], v[112:113], v[190:191]
	v_pk_mul_f32 v[102:103], v[102:103], v[110:111]
	v_pk_mul_f32 v[104:105], v[104:105], v[112:113]
	v_cvt_pk_bf16_f32 v184, v102, v103
	v_cvt_pk_bf16_f32 v185, v104, v105
	v_pk_mul_f32 v[188:189], v[106:107], v[192:193] op_sel_hi:[1,0]
	v_pk_mul_f32 v[190:191], v[108:109], v[192:193] op_sel_hi:[1,0]
	v_exp_f32_e32 v188, v188
	v_exp_f32_e32 v189, v189
	v_exp_f32_e32 v190, v190
	v_exp_f32_e32 v191, v191
	v_pk_add_f32 v[188:189], v[188:189], 1.0 op_sel_hi:[1,0]
	v_pk_add_f32 v[190:191], v[190:191], 1.0 op_sel_hi:[1,0]
	v_rcp_f32_e32 v188, v188
	v_rcp_f32_e32 v189, v189
	v_rcp_f32_e32 v190, v190
	v_rcp_f32_e32 v191, v191
	v_pk_mul_f32 v[106:107], v[106:107], v[188:189]
	v_pk_mul_f32 v[108:109], v[108:109], v[190:191]
	v_pk_mul_f32 v[98:99], v[98:99], v[106:107]
	v_pk_mul_f32 v[100:101], v[100:101], v[108:109]
	v_cvt_pk_bf16_f32 v186, v98, v99
	v_cvt_pk_bf16_f32 v187, v100, v101
	v_lshl_add_u64 v[182:183], v[182:183], 0, v[176:177]
	global_store_dwordx4 v[182:183], v[184:187], off
	v_or_b32_e32 v181, 32, v142
	v_mad_i64_i32 v[182:183], s[24:25], v181, s83, v[174:175]
	v_pk_mul_f32 v[94:95], v[94:95], v[242:243] op_sel_hi:[1,0]
	v_pk_mul_f32 v[96:97], v[96:97], v[242:243] op_sel_hi:[1,0]
	v_pk_mul_f32 v[90:91], v[90:91], v[242:243] op_sel_hi:[1,0]
	v_pk_mul_f32 v[92:93], v[92:93], v[242:243] op_sel_hi:[1,0]
	v_pk_mul_f32 v[86:87], v[86:87], v[242:243] op_sel_hi:[1,0]
	v_pk_mul_f32 v[88:89], v[88:89], v[242:243] op_sel_hi:[1,0]
	v_pk_mul_f32 v[82:83], v[82:83], v[242:243] op_sel_hi:[1,0]
	v_pk_mul_f32 v[84:85], v[84:85], v[242:243] op_sel_hi:[1,0]
	v_pk_mul_f32 v[188:189], v[94:95], v[192:193] op_sel_hi:[1,0]
	v_pk_mul_f32 v[190:191], v[96:97], v[192:193] op_sel_hi:[1,0]
	v_exp_f32_e32 v188, v188
	v_exp_f32_e32 v189, v189
	v_exp_f32_e32 v190, v190
	v_exp_f32_e32 v191, v191
	v_pk_add_f32 v[188:189], v[188:189], 1.0 op_sel_hi:[1,0]
	v_pk_add_f32 v[190:191], v[190:191], 1.0 op_sel_hi:[1,0]
	v_rcp_f32_e32 v188, v188
	v_rcp_f32_e32 v189, v189
	v_rcp_f32_e32 v190, v190
	v_rcp_f32_e32 v191, v191
	v_pk_mul_f32 v[94:95], v[94:95], v[188:189]
	v_pk_mul_f32 v[96:97], v[96:97], v[190:191]
	v_pk_mul_f32 v[86:87], v[86:87], v[94:95]
	v_pk_mul_f32 v[88:89], v[88:89], v[96:97]
	v_cvt_pk_bf16_f32 v184, v86, v87
	v_cvt_pk_bf16_f32 v185, v88, v89
	v_pk_mul_f32 v[188:189], v[90:91], v[192:193] op_sel_hi:[1,0]
	v_pk_mul_f32 v[190:191], v[92:93], v[192:193] op_sel_hi:[1,0]
	v_exp_f32_e32 v188, v188
	v_exp_f32_e32 v189, v189
	v_exp_f32_e32 v190, v190
	v_exp_f32_e32 v191, v191
	v_pk_add_f32 v[188:189], v[188:189], 1.0 op_sel_hi:[1,0]
	v_pk_add_f32 v[190:191], v[190:191], 1.0 op_sel_hi:[1,0]
	v_rcp_f32_e32 v188, v188
	v_rcp_f32_e32 v189, v189
	v_rcp_f32_e32 v190, v190
	v_rcp_f32_e32 v191, v191
	v_pk_mul_f32 v[90:91], v[90:91], v[188:189]
	v_pk_mul_f32 v[92:93], v[92:93], v[190:191]
	v_pk_mul_f32 v[82:83], v[82:83], v[90:91]
	v_pk_mul_f32 v[84:85], v[84:85], v[92:93]
	v_cvt_pk_bf16_f32 v186, v82, v83
	v_cvt_pk_bf16_f32 v187, v84, v85
	v_lshl_add_u64 v[182:183], v[182:183], 0, v[176:177]
	global_store_dwordx4 v[182:183], v[184:187], off
	v_or_b32_e32 v181, 48, v142
	v_mad_i64_i32 v[182:183], s[24:25], v181, s83, v[174:175]
	v_pk_mul_f32 v[78:79], v[78:79], v[244:245] op_sel_hi:[1,0]
	v_pk_mul_f32 v[80:81], v[80:81], v[244:245] op_sel_hi:[1,0]
	v_pk_mul_f32 v[74:75], v[74:75], v[244:245] op_sel_hi:[1,0]
	v_pk_mul_f32 v[76:77], v[76:77], v[244:245] op_sel_hi:[1,0]
	v_pk_mul_f32 v[70:71], v[70:71], v[244:245] op_sel_hi:[1,0]
	v_pk_mul_f32 v[72:73], v[72:73], v[244:245] op_sel_hi:[1,0]
	v_pk_mul_f32 v[66:67], v[66:67], v[244:245] op_sel_hi:[1,0]
	v_pk_mul_f32 v[68:69], v[68:69], v[244:245] op_sel_hi:[1,0]
	v_pk_mul_f32 v[188:189], v[78:79], v[192:193] op_sel_hi:[1,0]
	v_pk_mul_f32 v[190:191], v[80:81], v[192:193] op_sel_hi:[1,0]
	v_exp_f32_e32 v188, v188
	v_exp_f32_e32 v189, v189
	v_exp_f32_e32 v190, v190
	v_exp_f32_e32 v191, v191
	v_pk_add_f32 v[188:189], v[188:189], 1.0 op_sel_hi:[1,0]
	v_pk_add_f32 v[190:191], v[190:191], 1.0 op_sel_hi:[1,0]
	v_rcp_f32_e32 v188, v188
	v_rcp_f32_e32 v189, v189
	v_rcp_f32_e32 v190, v190
	v_rcp_f32_e32 v191, v191
	v_pk_mul_f32 v[78:79], v[78:79], v[188:189]
	v_pk_mul_f32 v[80:81], v[80:81], v[190:191]
	v_pk_mul_f32 v[70:71], v[70:71], v[78:79]
	v_pk_mul_f32 v[72:73], v[72:73], v[80:81]
	v_cvt_pk_bf16_f32 v184, v70, v71
	v_cvt_pk_bf16_f32 v185, v72, v73
	v_pk_mul_f32 v[188:189], v[74:75], v[192:193] op_sel_hi:[1,0]
	v_pk_mul_f32 v[190:191], v[76:77], v[192:193] op_sel_hi:[1,0]
	v_exp_f32_e32 v188, v188
	v_exp_f32_e32 v189, v189
	v_exp_f32_e32 v190, v190
	v_exp_f32_e32 v191, v191
	v_pk_add_f32 v[188:189], v[188:189], 1.0 op_sel_hi:[1,0]
	v_pk_add_f32 v[190:191], v[190:191], 1.0 op_sel_hi:[1,0]
	v_rcp_f32_e32 v188, v188
	v_rcp_f32_e32 v189, v189
	v_rcp_f32_e32 v190, v190
	v_rcp_f32_e32 v191, v191
	v_pk_mul_f32 v[74:75], v[74:75], v[188:189]
	v_pk_mul_f32 v[76:77], v[76:77], v[190:191]
	v_pk_mul_f32 v[66:67], v[66:67], v[74:75]
	v_pk_mul_f32 v[68:69], v[68:69], v[76:77]
	v_cvt_pk_bf16_f32 v186, v66, v67
	v_cvt_pk_bf16_f32 v187, v68, v69
	v_lshl_add_u64 v[182:183], v[182:183], 0, v[176:177]
	global_store_dwordx4 v[182:183], v[184:187], off
	v_add_u32_e32 v181, 0x80, v142
	v_mad_i64_i32 v[182:183], s[24:25], v181, s83, v[174:175]
	v_pk_mul_f32 v[62:63], v[62:63], v[246:247] op_sel_hi:[1,0]
	v_pk_mul_f32 v[64:65], v[64:65], v[246:247] op_sel_hi:[1,0]
	v_pk_mul_f32 v[58:59], v[58:59], v[246:247] op_sel_hi:[1,0]
	v_pk_mul_f32 v[60:61], v[60:61], v[246:247] op_sel_hi:[1,0]
	v_pk_mul_f32 v[54:55], v[54:55], v[246:247] op_sel_hi:[1,0]
	v_pk_mul_f32 v[56:57], v[56:57], v[246:247] op_sel_hi:[1,0]
	v_pk_mul_f32 v[50:51], v[50:51], v[246:247] op_sel_hi:[1,0]
	v_pk_mul_f32 v[52:53], v[52:53], v[246:247] op_sel_hi:[1,0]
	v_pk_mul_f32 v[188:189], v[62:63], v[192:193] op_sel_hi:[1,0]
	v_pk_mul_f32 v[190:191], v[64:65], v[192:193] op_sel_hi:[1,0]
	v_exp_f32_e32 v188, v188
	v_exp_f32_e32 v189, v189
	v_exp_f32_e32 v190, v190
	v_exp_f32_e32 v191, v191
	v_pk_add_f32 v[188:189], v[188:189], 1.0 op_sel_hi:[1,0]
	v_pk_add_f32 v[190:191], v[190:191], 1.0 op_sel_hi:[1,0]
	v_rcp_f32_e32 v188, v188
	v_rcp_f32_e32 v189, v189
	v_rcp_f32_e32 v190, v190
	v_rcp_f32_e32 v191, v191
	v_pk_mul_f32 v[62:63], v[62:63], v[188:189]
	v_pk_mul_f32 v[64:65], v[64:65], v[190:191]
	v_pk_mul_f32 v[54:55], v[54:55], v[62:63]
	v_pk_mul_f32 v[56:57], v[56:57], v[64:65]
	v_cvt_pk_bf16_f32 v184, v54, v55
	v_cvt_pk_bf16_f32 v185, v56, v57
	v_pk_mul_f32 v[188:189], v[58:59], v[192:193] op_sel_hi:[1,0]
	v_pk_mul_f32 v[190:191], v[60:61], v[192:193] op_sel_hi:[1,0]
	v_exp_f32_e32 v188, v188
	v_exp_f32_e32 v189, v189
	v_exp_f32_e32 v190, v190
	v_exp_f32_e32 v191, v191
	v_pk_add_f32 v[188:189], v[188:189], 1.0 op_sel_hi:[1,0]
	v_pk_add_f32 v[190:191], v[190:191], 1.0 op_sel_hi:[1,0]
	v_rcp_f32_e32 v188, v188
	v_rcp_f32_e32 v189, v189
	v_rcp_f32_e32 v190, v190
	v_rcp_f32_e32 v191, v191
	v_pk_mul_f32 v[58:59], v[58:59], v[188:189]
	v_pk_mul_f32 v[60:61], v[60:61], v[190:191]
	v_pk_mul_f32 v[50:51], v[50:51], v[58:59]
	v_pk_mul_f32 v[52:53], v[52:53], v[60:61]
	v_cvt_pk_bf16_f32 v186, v50, v51
	v_cvt_pk_bf16_f32 v187, v52, v53
	v_lshl_add_u64 v[182:183], v[182:183], 0, v[176:177]
	global_store_dwordx4 v[182:183], v[184:187], off
	v_add_u32_e32 v181, 0x90, v142
	v_mad_i64_i32 v[182:183], s[24:25], v181, s83, v[174:175]
	v_pk_mul_f32 v[46:47], v[46:47], v[248:249] op_sel_hi:[1,0]
	v_pk_mul_f32 v[48:49], v[48:49], v[248:249] op_sel_hi:[1,0]
	v_pk_mul_f32 v[42:43], v[42:43], v[248:249] op_sel_hi:[1,0]
	v_pk_mul_f32 v[44:45], v[44:45], v[248:249] op_sel_hi:[1,0]
	v_pk_mul_f32 v[38:39], v[38:39], v[248:249] op_sel_hi:[1,0]
	v_pk_mul_f32 v[40:41], v[40:41], v[248:249] op_sel_hi:[1,0]
	v_pk_mul_f32 v[34:35], v[34:35], v[248:249] op_sel_hi:[1,0]
	v_pk_mul_f32 v[36:37], v[36:37], v[248:249] op_sel_hi:[1,0]
	v_pk_mul_f32 v[188:189], v[46:47], v[192:193] op_sel_hi:[1,0]
	v_pk_mul_f32 v[190:191], v[48:49], v[192:193] op_sel_hi:[1,0]
	v_exp_f32_e32 v188, v188
	v_exp_f32_e32 v189, v189
	v_exp_f32_e32 v190, v190
	v_exp_f32_e32 v191, v191
	v_pk_add_f32 v[188:189], v[188:189], 1.0 op_sel_hi:[1,0]
	v_pk_add_f32 v[190:191], v[190:191], 1.0 op_sel_hi:[1,0]
	v_rcp_f32_e32 v188, v188
	v_rcp_f32_e32 v189, v189
	v_rcp_f32_e32 v190, v190
	v_rcp_f32_e32 v191, v191
	v_pk_mul_f32 v[46:47], v[46:47], v[188:189]
	v_pk_mul_f32 v[48:49], v[48:49], v[190:191]
	v_pk_mul_f32 v[38:39], v[38:39], v[46:47]
	v_pk_mul_f32 v[40:41], v[40:41], v[48:49]
	v_cvt_pk_bf16_f32 v184, v38, v39
	v_cvt_pk_bf16_f32 v185, v40, v41
	v_pk_mul_f32 v[188:189], v[42:43], v[192:193] op_sel_hi:[1,0]
	v_pk_mul_f32 v[190:191], v[44:45], v[192:193] op_sel_hi:[1,0]
	v_exp_f32_e32 v188, v188
	v_exp_f32_e32 v189, v189
	v_exp_f32_e32 v190, v190
	v_exp_f32_e32 v191, v191
	v_pk_add_f32 v[188:189], v[188:189], 1.0 op_sel_hi:[1,0]
	v_pk_add_f32 v[190:191], v[190:191], 1.0 op_sel_hi:[1,0]
	v_rcp_f32_e32 v188, v188
	v_rcp_f32_e32 v189, v189
	v_rcp_f32_e32 v190, v190
	v_rcp_f32_e32 v191, v191
	v_pk_mul_f32 v[42:43], v[42:43], v[188:189]
	v_pk_mul_f32 v[44:45], v[44:45], v[190:191]
	v_pk_mul_f32 v[34:35], v[34:35], v[42:43]
	v_pk_mul_f32 v[36:37], v[36:37], v[44:45]
	v_cvt_pk_bf16_f32 v186, v34, v35
	v_cvt_pk_bf16_f32 v187, v36, v37
	v_lshl_add_u64 v[182:183], v[182:183], 0, v[176:177]
	global_store_dwordx4 v[182:183], v[184:187], off
	v_add_u32_e32 v181, 0xa0, v142
	v_mad_i64_i32 v[182:183], s[24:25], v181, s83, v[174:175]
	v_pk_mul_f32 v[30:31], v[30:31], v[250:251] op_sel_hi:[1,0]
	v_pk_mul_f32 v[32:33], v[32:33], v[250:251] op_sel_hi:[1,0]
	v_pk_mul_f32 v[26:27], v[26:27], v[250:251] op_sel_hi:[1,0]
	v_pk_mul_f32 v[28:29], v[28:29], v[250:251] op_sel_hi:[1,0]
	v_pk_mul_f32 v[22:23], v[22:23], v[250:251] op_sel_hi:[1,0]
	v_pk_mul_f32 v[24:25], v[24:25], v[250:251] op_sel_hi:[1,0]
	v_pk_mul_f32 v[18:19], v[18:19], v[250:251] op_sel_hi:[1,0]
	v_pk_mul_f32 v[20:21], v[20:21], v[250:251] op_sel_hi:[1,0]
	v_pk_mul_f32 v[188:189], v[30:31], v[192:193] op_sel_hi:[1,0]
	v_pk_mul_f32 v[190:191], v[32:33], v[192:193] op_sel_hi:[1,0]
	v_exp_f32_e32 v188, v188
	v_exp_f32_e32 v189, v189
	v_exp_f32_e32 v190, v190
	v_exp_f32_e32 v191, v191
	v_pk_add_f32 v[188:189], v[188:189], 1.0 op_sel_hi:[1,0]
	v_pk_add_f32 v[190:191], v[190:191], 1.0 op_sel_hi:[1,0]
	v_rcp_f32_e32 v188, v188
	v_rcp_f32_e32 v189, v189
	v_rcp_f32_e32 v190, v190
	v_rcp_f32_e32 v191, v191
	v_pk_mul_f32 v[30:31], v[30:31], v[188:189]
	v_pk_mul_f32 v[32:33], v[32:33], v[190:191]
	v_pk_mul_f32 v[22:23], v[22:23], v[30:31]
	v_pk_mul_f32 v[24:25], v[24:25], v[32:33]
	v_cvt_pk_bf16_f32 v184, v22, v23
	v_cvt_pk_bf16_f32 v185, v24, v25
	v_pk_mul_f32 v[188:189], v[26:27], v[192:193] op_sel_hi:[1,0]
	v_pk_mul_f32 v[190:191], v[28:29], v[192:193] op_sel_hi:[1,0]
	v_exp_f32_e32 v188, v188
	v_exp_f32_e32 v189, v189
	v_exp_f32_e32 v190, v190
	v_exp_f32_e32 v191, v191
	v_pk_add_f32 v[188:189], v[188:189], 1.0 op_sel_hi:[1,0]
	v_pk_add_f32 v[190:191], v[190:191], 1.0 op_sel_hi:[1,0]
	v_rcp_f32_e32 v188, v188
	v_rcp_f32_e32 v189, v189
	v_rcp_f32_e32 v190, v190
	v_rcp_f32_e32 v191, v191
	v_pk_mul_f32 v[26:27], v[26:27], v[188:189]
	v_pk_mul_f32 v[28:29], v[28:29], v[190:191]
	v_pk_mul_f32 v[18:19], v[18:19], v[26:27]
	v_pk_mul_f32 v[20:21], v[20:21], v[28:29]
	v_cvt_pk_bf16_f32 v186, v18, v19
	v_cvt_pk_bf16_f32 v187, v20, v21
	v_lshl_add_u64 v[182:183], v[182:183], 0, v[176:177]
	global_store_dwordx4 v[182:183], v[184:187], off
	v_add_u32_e32 v181, 0xb0, v142
	v_mad_i64_i32 v[182:183], s[24:25], v181, s83, v[174:175]
	v_pk_mul_f32 v[14:15], v[14:15], v[252:253] op_sel_hi:[1,0]
	v_pk_mul_f32 v[16:17], v[16:17], v[252:253] op_sel_hi:[1,0]
	v_pk_mul_f32 v[10:11], v[10:11], v[252:253] op_sel_hi:[1,0]
	v_pk_mul_f32 v[12:13], v[12:13], v[252:253] op_sel_hi:[1,0]
	v_pk_mul_f32 v[6:7], v[6:7], v[252:253] op_sel_hi:[1,0]
	v_pk_mul_f32 v[8:9], v[8:9], v[252:253] op_sel_hi:[1,0]
	v_pk_mul_f32 v[2:3], v[2:3], v[252:253] op_sel_hi:[1,0]
	v_pk_mul_f32 v[4:5], v[4:5], v[252:253] op_sel_hi:[1,0]
	v_pk_mul_f32 v[188:189], v[14:15], v[192:193] op_sel_hi:[1,0]
	v_pk_mul_f32 v[190:191], v[16:17], v[192:193] op_sel_hi:[1,0]
	v_exp_f32_e32 v188, v188
	v_exp_f32_e32 v189, v189
	v_exp_f32_e32 v190, v190
	v_exp_f32_e32 v191, v191
	v_pk_add_f32 v[188:189], v[188:189], 1.0 op_sel_hi:[1,0]
	v_pk_add_f32 v[190:191], v[190:191], 1.0 op_sel_hi:[1,0]
	v_rcp_f32_e32 v188, v188
	v_rcp_f32_e32 v189, v189
	v_rcp_f32_e32 v190, v190
	v_rcp_f32_e32 v191, v191
	v_pk_mul_f32 v[14:15], v[14:15], v[188:189]
	v_pk_mul_f32 v[16:17], v[16:17], v[190:191]
	v_pk_mul_f32 v[6:7], v[6:7], v[14:15]
	v_pk_mul_f32 v[8:9], v[8:9], v[16:17]
	v_cvt_pk_bf16_f32 v184, v6, v7
	v_cvt_pk_bf16_f32 v185, v8, v9
	v_pk_mul_f32 v[188:189], v[10:11], v[192:193] op_sel_hi:[1,0]
	v_pk_mul_f32 v[190:191], v[12:13], v[192:193] op_sel_hi:[1,0]
	v_exp_f32_e32 v188, v188
	v_exp_f32_e32 v189, v189
	v_exp_f32_e32 v190, v190
	v_exp_f32_e32 v191, v191
	v_pk_add_f32 v[188:189], v[188:189], 1.0 op_sel_hi:[1,0]
	v_pk_add_f32 v[190:191], v[190:191], 1.0 op_sel_hi:[1,0]
	v_rcp_f32_e32 v188, v188
	v_rcp_f32_e32 v189, v189
	v_rcp_f32_e32 v190, v190
	v_rcp_f32_e32 v191, v191
	v_pk_mul_f32 v[10:11], v[10:11], v[188:189]
	v_pk_mul_f32 v[12:13], v[12:13], v[190:191]
	v_pk_mul_f32 v[2:3], v[2:3], v[10:11]
	v_pk_mul_f32 v[4:5], v[4:5], v[12:13]
	v_cvt_pk_bf16_f32 v186, v2, v3
	v_cvt_pk_bf16_f32 v187, v4, v5
	v_lshl_add_u64 v[182:183], v[182:183], 0, v[176:177]
	global_store_dwordx4 v[182:183], v[184:187], off
	s_mov_b64 s[24:25], -1
	s_andn2_b64 vcc, exec, s[2:3]
	s_cbranch_vccnz .LBB0_107
	s_andn2_b64 vcc, exec, s[6:7]
	s_cbranch_vccnz .LBB0_106
	s_barrier
	s_branch .LBB0_106

.LBB0_1171:
	s_or_b64 exec, exec, s[2:3]
	s_mov_b32 s100, -1
	v_writelane_b32 v255, s100, 48
	s_mov_b64 s[2:3], s[78:79]
	s_waitcnt lgkmcnt(0)
	s_barrier
	s_load_dwordx2 s[4:5], s[2:3], 0xf0
	s_mov_b32 s30, s76
	s_mov_b32 s31, s97
	v_mov_b32_e32 v1, v218
	s_cmpk_lt_i32 s31, 0xb00
	v_mov_b32_e32 v1, v218
	s_nop 0
	v_readfirstlane_b32 s3, v1
	s_cbranch_scc0 .LBB0_1187
	v_lshlrev_b32_e32 v2, 4, v1
	v_add_u32_e32 v3, 0x2000, v2
	v_ashrrev_i32_e32 v4, 31, v3
	v_lshrrev_b32_e32 v4, 22, v4
	v_add_u32_e32 v4, v3, v4
	s_waitcnt vmcnt(19)
	v_ashrrev_i32_e32 v10, 10, v4
	v_mul_i32_i24_e32 v4, 0x400, v10
	s_waitcnt lgkmcnt(0)
	s_add_u32 s34, s4, 0x9700000
	v_sub_u32_e32 v3, v3, v4
	s_addc_u32 s35, s5, 0
	v_readlane_b32 s2, v255, 10
	v_lshrrev_b32_e32 v4, 4, v3
	s_add_u32 s2, s4, s2
	v_readlane_b32 s6, v255, 11
	v_bitop3_b32 v3, v4, v3, 32 bitop3:0x6c
	s_addc_u32 s6, s5, s6
	v_ashrrev_i32_e32 v4, 31, v3
	s_add_u32 s36, s2, 0x2680000
	v_lshrrev_b32_e32 v4, 26, v4
	s_addc_u32 s37, s6, 0
	s_ashr_i32 s38, s31, 31
	v_add_u32_e32 v4, v3, v4
	v_lshlrev_b32_e32 v5, 3, v10
	v_ashrrev_i32_e32 v11, 6, v4
	v_and_b32_e32 v5, -16, v5
	s_lshr_b32 s2, s38, 29
	v_add_u32_e32 v5, v11, v5
	s_add_i32 s2, s31, s2
	s_ashr_i32 s12, s3, 6
	v_and_b32_e32 v6, 3, v11
	v_lshrrev_b32_e32 v7, 2, v5
	v_lshlrev_b32_e32 v8, 1, v5
	v_and_b32_e32 v4, 0xc0, v4
	s_ashr_i32 s6, s2, 3
	s_and_b32 s2, s2, -8
	s_ashr_i32 s13, s3, 8
	s_lshl_b32 s39, s12, 10
	v_and_or_b32 v6, v5, s69, v6
	v_and_b32_e32 v7, 4, v7
	v_and_b32_e32 v8, 24, v8
	v_sub_u32_e32 v3, v3, v4
	s_sub_i32 s2, s31, s2
	v_or3_b32 v6, v6, v7, v8
	v_lshlrev_b32_e32 v7, 5, v10
	v_ashrrev_i16_sdwa v3, v253, sext(v3) dst_sel:DWORD dst_unused:UNUSED_PAD src0_sel:DWORD src1_sel:BYTE_0
	s_cmp_lt_i32 s2, 0
	v_and_b32_e32 v7, 32, v7
	v_bfe_i32 v12, v3, 0, 16
	s_cselect_b32 s7, s70, 0x160
	v_add_lshl_u32 v3, v7, v12, 1
	s_mul_i32 s2, s2, s7
	v_lshl_add_u32 v130, v6, 11, v3
	v_lshl_add_u32 v132, v5, 11, v3
	v_bfe_i32 v3, v1, 27, 1
	s_add_i32 s2, s2, s6
	v_lshrrev_b32_e32 v3, 22, v3
	s_mul_hi_i32 s6, s2, 0x2e8ba2e9
	v_add_u32_e32 v3, v2, v3
	s_lshr_b32 s7, s6, 31
	s_ashr_i32 s6, s6, 4
	v_and_b32_e32 v3, 0xfffffc00, v3
	s_add_i32 s6, s6, s7
	v_sub_u32_e32 v2, v2, v3
	s_lshl_b32 s7, s6, 2
	s_mulk_i32 s6, 0x58
	v_lshrrev_b32_e32 v3, 4, v2
	v_ashrrev_i32_e32 v4, 31, v1
	s_sub_i32 s6, s2, s6
	v_bitop3_b32 v2, v3, v2, 32 bitop3:0x6c
	v_lshrrev_b32_e32 v4, 26, v4
	s_bfe_i32 s2, s6, 0x80000
	v_ashrrev_i32_e32 v3, 31, v2
	v_add_u32_e32 v4, v1, v4
	s_bfe_u32 s2, s2, 0x2000d
	v_lshrrev_b32_e32 v3, 26, v3
	v_ashrrev_i32_e32 v14, 6, v4
	s_add_i32 s8, s6, s2
	v_add_u32_e32 v3, v2, v3
	v_lshlrev_b32_e32 v4, 3, v14
	s_bfe_i32 s2, s8, 0x80000
	s_and_b32 s8, s8, 0xfc
	v_ashrrev_i32_e32 v13, 6, v3
	v_and_b32_e32 v4, -16, v4
	s_sub_i32 s6, s6, s8
	v_add_u32_e32 v4, v13, v4
	s_sext_i32_i16 s2, s2
	s_sext_i32_i8 s6, s6
	v_and_b32_e32 v5, 3, v13
	v_lshrrev_b32_e32 v6, 2, v4
	v_lshlrev_b32_e32 v7, 1, v4
	v_and_b32_e32 v3, 0xc0, v3
	s_lshr_b32 s2, s2, 2
	s_add_i32 s22, s7, s6
	v_and_or_b32 v5, v4, s69, v5
	v_and_b32_e32 v6, 4, v6
	v_and_b32_e32 v7, 24, v7
	v_sub_u32_e32 v2, v2, v3
	s_ashr_i32 s23, s22, 31
	s_bfe_i64 s[8:9], s[2:3], 0x100000
	v_or3_b32 v5, v5, v6, v7
	v_lshlrev_b32_e32 v6, 5, v14
	v_ashrrev_i16_sdwa v2, v253, sext(v2) dst_sel:DWORD dst_unused:UNUSED_PAD src0_sel:DWORD src1_sel:BYTE_0
	s_lshl_b64 s[6:7], s[22:23], 19
	s_lshl_b64 s[8:9], s[8:9], 19
	v_and_b32_e32 v6, 32, v6
	v_bfe_i32 v15, v2, 0, 16
	s_add_u32 s26, s36, s8
	v_add_lshl_u32 v2, v6, v15, 1
	s_addc_u32 s27, s37, s9
	s_add_i32 s40, s39, 0
	v_lshl_add_u32 v134, v5, 11, v2
	s_add_i32 m0, s40, 0x10000
	v_lshl_add_u32 v136, v4, 11, v2
	global_load_lds_dwordx4 v134, s[26:27]
	s_add_i32 m0, s40, 0x12000
	s_add_u32 s8, s26, 0x40000
	global_load_lds_dwordx4 v130, s[26:27]
	s_addc_u32 s9, s27, 0
	s_add_i32 m0, s40, 0x14000
	v_mov_b32_e32 v135, v0
	global_load_lds_dwordx4 v134, s[8:9]
	s_add_i32 m0, s40, 0x16000
	s_add_u32 s24, s34, s6
	s_addc_u32 s25, s35, s7
	s_add_i32 s41, s40, 0x2000
	global_load_lds_dwordx4 v130, s[8:9]
	s_mov_b32 m0, s40
	s_add_u32 s6, s24, 0x40000
	global_load_lds_dwordx4 v136, s[24:25]
	s_mov_b32 m0, s41
	s_addc_u32 s7, s25, 0
	s_add_i32 s42, s40, 0x4000
	global_load_lds_dwordx4 v132, s[24:25]
	s_mov_b32 m0, s42
	s_add_i32 s43, s40, 0x6000
	global_load_lds_dwordx4 v136, s[6:7]
	s_mov_b32 m0, s43
	v_mov_b32_e32 v131, v0
	global_load_lds_dwordx4 v132, s[6:7]
	v_mov_b32_e32 v137, v0
	v_mov_b32_e32 v133, v0
	s_cmp_eq_u32 s13, 1
	v_lshl_add_u64 v[8:9], s[26:27], 0, v[134:135]
	v_lshl_add_u64 v[6:7], s[26:27], 0, v[130:131]
	v_lshl_add_u64 v[2:3], s[24:25], 0, v[136:137]
	s_cselect_b64 s[6:7], -1, 0
	s_cmp_lg_u32 s13, 1
	v_lshl_add_u64 v[4:5], s[24:25], 0, v[132:133]
	s_cbranch_scc1 .LBB0_1174
	s_barrier

.LBB0_1183:
	v_mov_b32_e32 v143, v218
	s_lshl_b32 s15, s22, 8
	s_add_i32 s15, s15, s45
	v_and_or_b32 v142, v143, 15, s15
	s_lshl_b32 s15, s23, 7
	v_lshrrev_b32_e32 v143, 1, v143
	v_and_or_b32 v143, v143, 24, s15
	v_or_b32_e32 v148, s46, v143
	v_ashrrev_i32_e32 v143, 31, v142
	v_lshl_add_u64 v[144:145], v[142:143], 3, s[10:11]
	v_ashrrev_i32_e32 v149, 31, v148
	v_readlane_b32 s100, v255, 43
	s_nop 3
	s_cmp_eq_u32 s100, 0
	s_cbranch_scc1 .Lsw_skip_ffn2up
	v_readfirstlane_b32 s101, v218
	s_nop 3
	s_lshr_b32 s101, s101, 6
	s_cmp_lg_u32 s101, 0
	s_cbranch_scc1 .Lsw_join_ffn2up
	v_readlane_b32 s101, v255, 45
	s_nop 3
	v_mov_b32_e32 v172, s101
	v_readlane_b32 s101, v255, 46
	s_nop 3
	v_mov_b32_e32 v173, s101
	v_readlane_b32 s100, v255, 44
	s_nop 3
	s_lshl_b32 s100, s100, 3

.Lsw_skip_ffn2up:
	v_lshlrev_b64 v[176:177], 1, v[148:149]
	v_mov_b64_e32 v[174:175], s[8:9]
	v_readlane_b32 s100, v255, 48
	s_nop 3
	s_cmp_eq_u32 s100, s22
	s_cbranch_scc1 .Lrs_hit_b
	global_load_dwordx2 v[146:147], v[144:145], off
	global_load_dwordx2 v[158:159], v[144:145], off offset:128
	global_load_dwordx2 v[160:161], v[144:145], off offset:256
	global_load_dwordx2 v[162:163], v[144:145], off offset:384
	global_load_dwordx2 v[164:165], v[144:145], off offset:1024
	global_load_dwordx2 v[166:167], v[144:145], off offset:1152
	global_load_dwordx2 v[168:169], v[144:145], off offset:1280
	global_load_dwordx2 v[170:171], v[144:145], off offset:1408
	v_writelane_b32 v255, s22, 48
	s_waitcnt vmcnt(0)
	v_ffbh_u32_e32 v180, v147
	v_min_u32_e32 v180, 32, v180
	v_lshlrev_b64 v[178:179], v180, v[146:147]
	v_min_u32_e32 v178, 1, v178
	v_or_b32_e32 v178, v179, v178
	v_cvt_f32_u32_e32 v178, v178
	v_sub_u32_e32 v179, 32, v180
	v_ldexp_f32 v178, v178, v179
	v_fmamk_f32 v178, v178, 0x31800000, v219
	v_rsq_f32_e32 v238, v178
	v_ffbh_u32_e32 v180, v159
	v_min_u32_e32 v180, 32, v180
	v_lshlrev_b64 v[178:179], v180, v[158:159]
	v_min_u32_e32 v178, 1, v178
	v_or_b32_e32 v178, v179, v178
	v_cvt_f32_u32_e32 v178, v178
	v_sub_u32_e32 v179, 32, v180
	v_ldexp_f32 v178, v178, v179
	v_fmamk_f32 v178, v178, 0x31800000, v219
	v_rsq_f32_e32 v240, v178
	v_ffbh_u32_e32 v180, v161
	v_min_u32_e32 v180, 32, v180
	v_lshlrev_b64 v[178:179], v180, v[160:161]
	v_min_u32_e32 v178, 1, v178
	v_or_b32_e32 v178, v179, v178
	v_cvt_f32_u32_e32 v178, v178
	v_sub_u32_e32 v179, 32, v180
	v_ldexp_f32 v178, v178, v179
	v_fmamk_f32 v178, v178, 0x31800000, v219
	v_rsq_f32_e32 v242, v178
	v_ffbh_u32_e32 v180, v163
	v_min_u32_e32 v180, 32, v180
	v_lshlrev_b64 v[178:179], v180, v[162:163]
	v_min_u32_e32 v178, 1, v178
	v_or_b32_e32 v178, v179, v178
	v_cvt_f32_u32_e32 v178, v178
	v_sub_u32_e32 v179, 32, v180
	v_ldexp_f32 v178, v178, v179
	v_fmamk_f32 v178, v178, 0x31800000, v219
	v_rsq_f32_e32 v244, v178
	v_ffbh_u32_e32 v180, v165
	v_min_u32_e32 v180, 32, v180
	v_lshlrev_b64 v[178:179], v180, v[164:165]
	v_min_u32_e32 v178, 1, v178
	v_or_b32_e32 v178, v179, v178
	v_cvt_f32_u32_e32 v178, v178
	v_sub_u32_e32 v179, 32, v180
	v_ldexp_f32 v178, v178, v179
	v_fmamk_f32 v178, v178, 0x31800000, v219
	v_rsq_f32_e32 v246, v178
	v_ffbh_u32_e32 v180, v167
	v_min_u32_e32 v180, 32, v180
	v_lshlrev_b64 v[178:179], v180, v[166:167]
	v_min_u32_e32 v178, 1, v178
	v_or_b32_e32 v178, v179, v178
	v_cvt_f32_u32_e32 v178, v178
	v_sub_u32_e32 v179, 32, v180
	v_ldexp_f32 v178, v178, v179
	v_fmamk_f32 v178, v178, 0x31800000, v219
	v_rsq_f32_e32 v248, v178
	v_ffbh_u32_e32 v180, v169
	v_min_u32_e32 v180, 32, v180
	v_lshlrev_b64 v[178:179], v180, v[168:169]
	v_min_u32_e32 v178, 1, v178
	v_or_b32_e32 v178, v179, v178
	v_cvt_f32_u32_e32 v178, v178
	v_sub_u32_e32 v179, 32, v180
	v_ldexp_f32 v178, v178, v179
	v_fmamk_f32 v178, v178, 0x31800000, v219
	v_rsq_f32_e32 v250, v178
	v_ffbh_u32_e32 v180, v171
	v_min_u32_e32 v180, 32, v180
	v_lshlrev_b64 v[178:179], v180, v[170:171]
	v_min_u32_e32 v178, 1, v178
	v_or_b32_e32 v178, v179, v178
	v_cvt_f32_u32_e32 v178, v178
	v_sub_u32_e32 v179, 32, v180
	v_ldexp_f32 v178, v178, v179
	v_fmamk_f32 v178, v178, 0x31800000, v219
	v_rsq_f32_e32 v252, v178
.Lrs_hit_b:
	v_mov_b32_e32 v192, 0xbfb8aa3b
	v_mad_i64_i32 v[182:183], s[22:23], v142, s83, v[174:175]
	v_pk_mul_f32 v[126:127], v[126:127], v[238:239] op_sel_hi:[1,0]
	v_pk_mul_f32 v[128:129], v[128:129], v[238:239] op_sel_hi:[1,0]
	v_pk_mul_f32 v[122:123], v[122:123], v[238:239] op_sel_hi:[1,0]
	v_pk_mul_f32 v[124:125], v[124:125], v[238:239] op_sel_hi:[1,0]
	v_pk_mul_f32 v[118:119], v[118:119], v[238:239] op_sel_hi:[1,0]
	v_pk_mul_f32 v[120:121], v[120:121], v[238:239] op_sel_hi:[1,0]
	v_pk_mul_f32 v[114:115], v[114:115], v[238:239] op_sel_hi:[1,0]
	v_pk_mul_f32 v[116:117], v[116:117], v[238:239] op_sel_hi:[1,0]
	v_pk_mul_f32 v[188:189], v[126:127], v[192:193] op_sel_hi:[1,0]
	v_pk_mul_f32 v[190:191], v[128:129], v[192:193] op_sel_hi:[1,0]
	v_exp_f32_e32 v188, v188
	v_exp_f32_e32 v189, v189
	v_exp_f32_e32 v190, v190
	v_exp_f32_e32 v191, v191
	v_pk_add_f32 v[188:189], v[188:189], 1.0 op_sel_hi:[1,0]
	v_pk_add_f32 v[190:191], v[190:191], 1.0 op_sel_hi:[1,0]
	v_rcp_f32_e32 v188, v188
	v_rcp_f32_e32 v189, v189
	v_rcp_f32_e32 v190, v190
	v_rcp_f32_e32 v191, v191
	v_pk_mul_f32 v[126:127], v[126:127], v[188:189]
	v_pk_mul_f32 v[128:129], v[128:129], v[190:191]
	v_pk_mul_f32 v[118:119], v[118:119], v[126:127]
	v_pk_mul_f32 v[120:121], v[120:121], v[128:129]
	v_cvt_pk_bf16_f32 v184, v118, v119
	v_cvt_pk_bf16_f32 v185, v120, v121
	v_pk_mul_f32 v[188:189], v[122:123], v[192:193] op_sel_hi:[1,0]
	v_pk_mul_f32 v[190:191], v[124:125], v[192:193] op_sel_hi:[1,0]
	v_exp_f32_e32 v188, v188
	v_exp_f32_e32 v189, v189
	v_exp_f32_e32 v190, v190
	v_exp_f32_e32 v191, v191
	v_pk_add_f32 v[188:189], v[188:189], 1.0 op_sel_hi:[1,0]
	v_pk_add_f32 v[190:191], v[190:191], 1.0 op_sel_hi:[1,0]
	v_rcp_f32_e32 v188, v188
	v_rcp_f32_e32 v189, v189
	v_rcp_f32_e32 v190, v190
	v_rcp_f32_e32 v191, v191
	v_pk_mul_f32 v[122:123], v[122:123], v[188:189]
	v_pk_mul_f32 v[124:125], v[124:125], v[190:191]
	v_pk_mul_f32 v[114:115], v[114:115], v[122:123]
	v_pk_mul_f32 v[116:117], v[116:117], v[124:125]
	v_cvt_pk_bf16_f32 v186, v114, v115
	v_cvt_pk_bf16_f32 v187, v116, v117
	v_lshl_add_u64 v[182:183], v[182:183], 0, v[176:177]
	global_store_dwordx4 v[182:183], v[184:187], off
	v_or_b32_e32 v181, 16, v142
	v_mad_i64_i32 v[182:183], s[22:23], v181, s83, v[174:175]
	v_pk_mul_f32 v[110:111], v[110:111], v[240:241] op_sel_hi:[1,0]
	v_pk_mul_f32 v[112:113], v[112:113], v[240:241] op_sel_hi:[1,0]
	v_pk_mul_f32 v[106:107], v[106:107], v[240:241] op_sel_hi:[1,0]
	v_pk_mul_f32 v[108:109], v[108:109], v[240:241] op_sel_hi:[1,0]
	v_pk_mul_f32 v[102:103], v[102:103], v[240:241] op_sel_hi:[1,0]
	v_pk_mul_f32 v[104:105], v[104:105], v[240:241] op_sel_hi:[1,0]
	v_pk_mul_f32 v[98:99], v[98:99], v[240:241] op_sel_hi:[1,0]
	v_pk_mul_f32 v[100:101], v[100:101], v[240:241] op_sel_hi:[1,0]
	v_pk_mul_f32 v[188:189], v[110:111], v[192:193] op_sel_hi:[1,0]
	v_pk_mul_f32 v[190:191], v[112:113], v[192:193] op_sel_hi:[1,0]
	v_exp_f32_e32 v188, v188
	v_exp_f32_e32 v189, v189
	v_exp_f32_e32 v190, v190
	v_exp_f32_e32 v191, v191
	v_pk_add_f32 v[188:189], v[188:189], 1.0 op_sel_hi:[1,0]
	v_pk_add_f32 v[190:191], v[190:191], 1.0 op_sel_hi:[1,0]
	v_rcp_f32_e32 v188, v188
	v_rcp_f32_e32 v189, v189
	v_rcp_f32_e32 v190, v190
	v_rcp_f32_e32 v191, v191
	v_pk_mul_f32 v[110:111], v[110:111], v[188:189]
	v_pk_mul_f32 v[112:113], v[112:113], v[190:191]
	v_pk_mul_f32 v[102:103], v[102:103], v[110:111]
	v_pk_mul_f32 v[104:105], v[104:105], v[112:113]
	v_cvt_pk_bf16_f32 v184, v102, v103
	v_cvt_pk_bf16_f32 v185, v104, v105
	v_pk_mul_f32 v[188:189], v[106:107], v[192:193] op_sel_hi:[1,0]
	v_pk_mul_f32 v[190:191], v[108:109], v[192:193] op_sel_hi:[1,0]
	v_exp_f32_e32 v188, v188
	v_exp_f32_e32 v189, v189
	v_exp_f32_e32 v190, v190
	v_exp_f32_e32 v191, v191
	v_pk_add_f32 v[188:189], v[188:189], 1.0 op_sel_hi:[1,0]
	v_pk_add_f32 v[190:191], v[190:191], 1.0 op_sel_hi:[1,0]
	v_rcp_f32_e32 v188, v188
	v_rcp_f32_e32 v189, v189
	v_rcp_f32_e32 v190, v190
	v_rcp_f32_e32 v191, v191
	v_pk_mul_f32 v[106:107], v[106:107], v[188:189]
	v_pk_mul_f32 v[108:109], v[108:109], v[190:191]
	v_pk_mul_f32 v[98:99], v[98:99], v[106:107]
	v_pk_mul_f32 v[100:101], v[100:101], v[108:109]
	v_cvt_pk_bf16_f32 v186, v98, v99
	v_cvt_pk_bf16_f32 v187, v100, v101
	v_lshl_add_u64 v[182:183], v[182:183], 0, v[176:177]
	global_store_dwordx4 v[182:183], v[184:187], off
	v_or_b32_e32 v181, 32, v142
	v_mad_i64_i32 v[182:183], s[22:23], v181, s83, v[174:175]
	v_pk_mul_f32 v[94:95], v[94:95], v[242:243] op_sel_hi:[1,0]
	v_pk_mul_f32 v[96:97], v[96:97], v[242:243] op_sel_hi:[1,0]
	v_pk_mul_f32 v[90:91], v[90:91], v[242:243] op_sel_hi:[1,0]
	v_pk_mul_f32 v[92:93], v[92:93], v[242:243] op_sel_hi:[1,0]
	v_pk_mul_f32 v[86:87], v[86:87], v[242:243] op_sel_hi:[1,0]
	v_pk_mul_f32 v[88:89], v[88:89], v[242:243] op_sel_hi:[1,0]
	v_pk_mul_f32 v[82:83], v[82:83], v[242:243] op_sel_hi:[1,0]
	v_pk_mul_f32 v[84:85], v[84:85], v[242:243] op_sel_hi:[1,0]
	v_pk_mul_f32 v[188:189], v[94:95], v[192:193] op_sel_hi:[1,0]
	v_pk_mul_f32 v[190:191], v[96:97], v[192:193] op_sel_hi:[1,0]
	v_exp_f32_e32 v188, v188
	v_exp_f32_e32 v189, v189
	v_exp_f32_e32 v190, v190
	v_exp_f32_e32 v191, v191
	v_pk_add_f32 v[188:189], v[188:189], 1.0 op_sel_hi:[1,0]
	v_pk_add_f32 v[190:191], v[190:191], 1.0 op_sel_hi:[1,0]
	v_rcp_f32_e32 v188, v188
	v_rcp_f32_e32 v189, v189
	v_rcp_f32_e32 v190, v190
	v_rcp_f32_e32 v191, v191
	v_pk_mul_f32 v[94:95], v[94:95], v[188:189]
	v_pk_mul_f32 v[96:97], v[96:97], v[190:191]
	v_pk_mul_f32 v[86:87], v[86:87], v[94:95]
	v_pk_mul_f32 v[88:89], v[88:89], v[96:97]
	v_cvt_pk_bf16_f32 v184, v86, v87
	v_cvt_pk_bf16_f32 v185, v88, v89
	v_pk_mul_f32 v[188:189], v[90:91], v[192:193] op_sel_hi:[1,0]
	v_pk_mul_f32 v[190:191], v[92:93], v[192:193] op_sel_hi:[1,0]
	v_exp_f32_e32 v188, v188
	v_exp_f32_e32 v189, v189
	v_exp_f32_e32 v190, v190
	v_exp_f32_e32 v191, v191
	v_pk_add_f32 v[188:189], v[188:189], 1.0 op_sel_hi:[1,0]
	v_pk_add_f32 v[190:191], v[190:191], 1.0 op_sel_hi:[1,0]
	v_rcp_f32_e32 v188, v188
	v_rcp_f32_e32 v189, v189
	v_rcp_f32_e32 v190, v190
	v_rcp_f32_e32 v191, v191
	v_pk_mul_f32 v[90:91], v[90:91], v[188:189]
	v_pk_mul_f32 v[92:93], v[92:93], v[190:191]
	v_pk_mul_f32 v[82:83], v[82:83], v[90:91]
	v_pk_mul_f32 v[84:85], v[84:85], v[92:93]
	v_cvt_pk_bf16_f32 v186, v82, v83
	v_cvt_pk_bf16_f32 v187, v84, v85
	v_lshl_add_u64 v[182:183], v[182:183], 0, v[176:177]
	global_store_dwordx4 v[182:183], v[184:187], off
	v_or_b32_e32 v181, 48, v142
	v_mad_i64_i32 v[182:183], s[22:23], v181, s83, v[174:175]
	v_pk_mul_f32 v[78:79], v[78:79], v[244:245] op_sel_hi:[1,0]
	v_pk_mul_f32 v[80:81], v[80:81], v[244:245] op_sel_hi:[1,0]
	v_pk_mul_f32 v[74:75], v[74:75], v[244:245] op_sel_hi:[1,0]
	v_pk_mul_f32 v[76:77], v[76:77], v[244:245] op_sel_hi:[1,0]
	v_pk_mul_f32 v[70:71], v[70:71], v[244:245] op_sel_hi:[1,0]
	v_pk_mul_f32 v[72:73], v[72:73], v[244:245] op_sel_hi:[1,0]
	v_pk_mul_f32 v[66:67], v[66:67], v[244:245] op_sel_hi:[1,0]
	v_pk_mul_f32 v[68:69], v[68:69], v[244:245] op_sel_hi:[1,0]
	v_pk_mul_f32 v[188:189], v[78:79], v[192:193] op_sel_hi:[1,0]
	v_pk_mul_f32 v[190:191], v[80:81], v[192:193] op_sel_hi:[1,0]
	v_exp_f32_e32 v188, v188
	v_exp_f32_e32 v189, v189
	v_exp_f32_e32 v190, v190
	v_exp_f32_e32 v191, v191
	v_pk_add_f32 v[188:189], v[188:189], 1.0 op_sel_hi:[1,0]
	v_pk_add_f32 v[190:191], v[190:191], 1.0 op_sel_hi:[1,0]
	v_rcp_f32_e32 v188, v188
	v_rcp_f32_e32 v189, v189
	v_rcp_f32_e32 v190, v190
	v_rcp_f32_e32 v191, v191
	v_pk_mul_f32 v[78:79], v[78:79], v[188:189]
	v_pk_mul_f32 v[80:81], v[80:81], v[190:191]
	v_pk_mul_f32 v[70:71], v[70:71], v[78:79]
	v_pk_mul_f32 v[72:73], v[72:73], v[80:81]
	v_cvt_pk_bf16_f32 v184, v70, v71
	v_cvt_pk_bf16_f32 v185, v72, v73
	v_pk_mul_f32 v[188:189], v[74:75], v[192:193] op_sel_hi:[1,0]
	v_pk_mul_f32 v[190:191], v[76:77], v[192:193] op_sel_hi:[1,0]
	v_exp_f32_e32 v188, v188
	v_exp_f32_e32 v189, v189
	v_exp_f32_e32 v190, v190
	v_exp_f32_e32 v191, v191
	v_pk_add_f32 v[188:189], v[188:189], 1.0 op_sel_hi:[1,0]
	v_pk_add_f32 v[190:191], v[190:191], 1.0 op_sel_hi:[1,0]
	v_rcp_f32_e32 v188, v188
	v_rcp_f32_e32 v189, v189
	v_rcp_f32_e32 v190, v190
	v_rcp_f32_e32 v191, v191
	v_pk_mul_f32 v[74:75], v[74:75], v[188:189]
	v_pk_mul_f32 v[76:77], v[76:77], v[190:191]
	v_pk_mul_f32 v[66:67], v[66:67], v[74:75]
	v_pk_mul_f32 v[68:69], v[68:69], v[76:77]
	v_cvt_pk_bf16_f32 v186, v66, v67
	v_cvt_pk_bf16_f32 v187, v68, v69
	v_lshl_add_u64 v[182:183], v[182:183], 0, v[176:177]
	global_store_dwordx4 v[182:183], v[184:187], off
	v_add_u32_e32 v181, 0x80, v142
	v_mad_i64_i32 v[182:183], s[22:23], v181, s83, v[174:175]
	v_pk_mul_f32 v[62:63], v[62:63], v[246:247] op_sel_hi:[1,0]
	v_pk_mul_f32 v[64:65], v[64:65], v[246:247] op_sel_hi:[1,0]
	v_pk_mul_f32 v[58:59], v[58:59], v[246:247] op_sel_hi:[1,0]
	v_pk_mul_f32 v[60:61], v[60:61], v[246:247] op_sel_hi:[1,0]
	v_pk_mul_f32 v[54:55], v[54:55], v[246:247] op_sel_hi:[1,0]
	v_pk_mul_f32 v[56:57], v[56:57], v[246:247] op_sel_hi:[1,0]
	v_pk_mul_f32 v[50:51], v[50:51], v[246:247] op_sel_hi:[1,0]
	v_pk_mul_f32 v[52:53], v[52:53], v[246:247] op_sel_hi:[1,0]
	v_pk_mul_f32 v[188:189], v[62:63], v[192:193] op_sel_hi:[1,0]
	v_pk_mul_f32 v[190:191], v[64:65], v[192:193] op_sel_hi:[1,0]
	v_exp_f32_e32 v188, v188
	v_exp_f32_e32 v189, v189
	v_exp_f32_e32 v190, v190
	v_exp_f32_e32 v191, v191
	v_pk_add_f32 v[188:189], v[188:189], 1.0 op_sel_hi:[1,0]
	v_pk_add_f32 v[190:191], v[190:191], 1.0 op_sel_hi:[1,0]
	v_rcp_f32_e32 v188, v188
	v_rcp_f32_e32 v189, v189
	v_rcp_f32_e32 v190, v190
	v_rcp_f32_e32 v191, v191
	v_pk_mul_f32 v[62:63], v[62:63], v[188:189]
	v_pk_mul_f32 v[64:65], v[64:65], v[190:191]
	v_pk_mul_f32 v[54:55], v[54:55], v[62:63]
	v_pk_mul_f32 v[56:57], v[56:57], v[64:65]
	v_cvt_pk_bf16_f32 v184, v54, v55
	v_cvt_pk_bf16_f32 v185, v56, v57
	v_pk_mul_f32 v[188:189], v[58:59], v[192:193] op_sel_hi:[1,0]
	v_pk_mul_f32 v[190:191], v[60:61], v[192:193] op_sel_hi:[1,0]
	v_exp_f32_e32 v188, v188
	v_exp_f32_e32 v189, v189
	v_exp_f32_e32 v190, v190
	v_exp_f32_e32 v191, v191
	v_pk_add_f32 v[188:189], v[188:189], 1.0 op_sel_hi:[1,0]
	v_pk_add_f32 v[190:191], v[190:191], 1.0 op_sel_hi:[1,0]
	v_rcp_f32_e32 v188, v188
	v_rcp_f32_e32 v189, v189
	v_rcp_f32_e32 v190, v190
	v_rcp_f32_e32 v191, v191
	v_pk_mul_f32 v[58:59], v[58:59], v[188:189]
	v_pk_mul_f32 v[60:61], v[60:61], v[190:191]
	v_pk_mul_f32 v[50:51], v[50:51], v[58:59]
	v_pk_mul_f32 v[52:53], v[52:53], v[60:61]
	v_cvt_pk_bf16_f32 v186, v50, v51
	v_cvt_pk_bf16_f32 v187, v52, v53
	v_lshl_add_u64 v[182:183], v[182:183], 0, v[176:177]
	global_store_dwordx4 v[182:183], v[184:187], off
	v_add_u32_e32 v181, 0x90, v142
	v_mad_i64_i32 v[182:183], s[22:23], v181, s83, v[174:175]
	v_pk_mul_f32 v[46:47], v[46:47], v[248:249] op_sel_hi:[1,0]
	v_pk_mul_f32 v[48:49], v[48:49], v[248:249] op_sel_hi:[1,0]
	v_pk_mul_f32 v[42:43], v[42:43], v[248:249] op_sel_hi:[1,0]
	v_pk_mul_f32 v[44:45], v[44:45], v[248:249] op_sel_hi:[1,0]
	v_pk_mul_f32 v[38:39], v[38:39], v[248:249] op_sel_hi:[1,0]
	v_pk_mul_f32 v[40:41], v[40:41], v[248:249] op_sel_hi:[1,0]
	v_pk_mul_f32 v[34:35], v[34:35], v[248:249] op_sel_hi:[1,0]
	v_pk_mul_f32 v[36:37], v[36:37], v[248:249] op_sel_hi:[1,0]
	v_pk_mul_f32 v[188:189], v[46:47], v[192:193] op_sel_hi:[1,0]
	v_pk_mul_f32 v[190:191], v[48:49], v[192:193] op_sel_hi:[1,0]
	v_exp_f32_e32 v188, v188
	v_exp_f32_e32 v189, v189
	v_exp_f32_e32 v190, v190
	v_exp_f32_e32 v191, v191
	v_pk_add_f32 v[188:189], v[188:189], 1.0 op_sel_hi:[1,0]
	v_pk_add_f32 v[190:191], v[190:191], 1.0 op_sel_hi:[1,0]
	v_rcp_f32_e32 v188, v188
	v_rcp_f32_e32 v189, v189
	v_rcp_f32_e32 v190, v190
	v_rcp_f32_e32 v191, v191
	v_pk_mul_f32 v[46:47], v[46:47], v[188:189]
	v_pk_mul_f32 v[48:49], v[48:49], v[190:191]
	v_pk_mul_f32 v[38:39], v[38:39], v[46:47]
	v_pk_mul_f32 v[40:41], v[40:41], v[48:49]
	v_cvt_pk_bf16_f32 v184, v38, v39
	v_cvt_pk_bf16_f32 v185, v40, v41
	v_pk_mul_f32 v[188:189], v[42:43], v[192:193] op_sel_hi:[1,0]
	v_pk_mul_f32 v[190:191], v[44:45], v[192:193] op_sel_hi:[1,0]
	v_exp_f32_e32 v188, v188
	v_exp_f32_e32 v189, v189
	v_exp_f32_e32 v190, v190
	v_exp_f32_e32 v191, v191
	v_pk_add_f32 v[188:189], v[188:189], 1.0 op_sel_hi:[1,0]
	v_pk_add_f32 v[190:191], v[190:191], 1.0 op_sel_hi:[1,0]
	v_rcp_f32_e32 v188, v188
	v_rcp_f32_e32 v189, v189
	v_rcp_f32_e32 v190, v190
	v_rcp_f32_e32 v191, v191
	v_pk_mul_f32 v[42:43], v[42:43], v[188:189]
	v_pk_mul_f32 v[44:45], v[44:45], v[190:191]
	v_pk_mul_f32 v[34:35], v[34:35], v[42:43]
	v_pk_mul_f32 v[36:37], v[36:37], v[44:45]
	v_cvt_pk_bf16_f32 v186, v34, v35
	v_cvt_pk_bf16_f32 v187, v36, v37
	v_lshl_add_u64 v[182:183], v[182:183], 0, v[176:177]
	global_store_dwordx4 v[182:183], v[184:187], off
	v_add_u32_e32 v181, 0xa0, v142
	v_mad_i64_i32 v[182:183], s[22:23], v181, s83, v[174:175]
	v_pk_mul_f32 v[30:31], v[30:31], v[250:251] op_sel_hi:[1,0]
	v_pk_mul_f32 v[32:33], v[32:33], v[250:251] op_sel_hi:[1,0]
	v_pk_mul_f32 v[26:27], v[26:27], v[250:251] op_sel_hi:[1,0]
	v_pk_mul_f32 v[28:29], v[28:29], v[250:251] op_sel_hi:[1,0]
	v_pk_mul_f32 v[22:23], v[22:23], v[250:251] op_sel_hi:[1,0]
	v_pk_mul_f32 v[24:25], v[24:25], v[250:251] op_sel_hi:[1,0]
	v_pk_mul_f32 v[18:19], v[18:19], v[250:251] op_sel_hi:[1,0]
	v_pk_mul_f32 v[20:21], v[20:21], v[250:251] op_sel_hi:[1,0]
	v_pk_mul_f32 v[188:189], v[30:31], v[192:193] op_sel_hi:[1,0]
	v_pk_mul_f32 v[190:191], v[32:33], v[192:193] op_sel_hi:[1,0]
	v_exp_f32_e32 v188, v188
	v_exp_f32_e32 v189, v189
	v_exp_f32_e32 v190, v190
	v_exp_f32_e32 v191, v191
	v_pk_add_f32 v[188:189], v[188:189], 1.0 op_sel_hi:[1,0]
	v_pk_add_f32 v[190:191], v[190:191], 1.0 op_sel_hi:[1,0]
	v_rcp_f32_e32 v188, v188
	v_rcp_f32_e32 v189, v189
	v_rcp_f32_e32 v190, v190
	v_rcp_f32_e32 v191, v191
	v_pk_mul_f32 v[30:31], v[30:31], v[188:189]
	v_pk_mul_f32 v[32:33], v[32:33], v[190:191]
	v_pk_mul_f32 v[22:23], v[22:23], v[30:31]
	v_pk_mul_f32 v[24:25], v[24:25], v[32:33]
	v_cvt_pk_bf16_f32 v184, v22, v23
	v_cvt_pk_bf16_f32 v185, v24, v25
	v_pk_mul_f32 v[188:189], v[26:27], v[192:193] op_sel_hi:[1,0]
	v_pk_mul_f32 v[190:191], v[28:29], v[192:193] op_sel_hi:[1,0]
	v_exp_f32_e32 v188, v188
	v_exp_f32_e32 v189, v189
	v_exp_f32_e32 v190, v190
	v_exp_f32_e32 v191, v191
	v_pk_add_f32 v[188:189], v[188:189], 1.0 op_sel_hi:[1,0]
	v_pk_add_f32 v[190:191], v[190:191], 1.0 op_sel_hi:[1,0]
	v_rcp_f32_e32 v188, v188
	v_rcp_f32_e32 v189, v189
	v_rcp_f32_e32 v190, v190
	v_rcp_f32_e32 v191, v191
	v_pk_mul_f32 v[26:27], v[26:27], v[188:189]
	v_pk_mul_f32 v[28:29], v[28:29], v[190:191]
	v_pk_mul_f32 v[18:19], v[18:19], v[26:27]
	v_pk_mul_f32 v[20:21], v[20:21], v[28:29]
	v_cvt_pk_bf16_f32 v186, v18, v19
	v_cvt_pk_bf16_f32 v187, v20, v21
	v_lshl_add_u64 v[182:183], v[182:183], 0, v[176:177]
	global_store_dwordx4 v[182:183], v[184:187], off
	v_add_u32_e32 v181, 0xb0, v142
	v_mad_i64_i32 v[182:183], s[22:23], v181, s83, v[174:175]
	v_pk_mul_f32 v[14:15], v[14:15], v[252:253] op_sel_hi:[1,0]
	v_pk_mul_f32 v[16:17], v[16:17], v[252:253] op_sel_hi:[1,0]
	v_pk_mul_f32 v[10:11], v[10:11], v[252:253] op_sel_hi:[1,0]
	v_pk_mul_f32 v[12:13], v[12:13], v[252:253] op_sel_hi:[1,0]
	v_pk_mul_f32 v[6:7], v[6:7], v[252:253] op_sel_hi:[1,0]
	v_pk_mul_f32 v[8:9], v[8:9], v[252:253] op_sel_hi:[1,0]
	v_pk_mul_f32 v[2:3], v[2:3], v[252:253] op_sel_hi:[1,0]
	v_pk_mul_f32 v[4:5], v[4:5], v[252:253] op_sel_hi:[1,0]
	v_pk_mul_f32 v[188:189], v[14:15], v[192:193] op_sel_hi:[1,0]
	v_pk_mul_f32 v[190:191], v[16:17], v[192:193] op_sel_hi:[1,0]
	v_exp_f32_e32 v188, v188
	v_exp_f32_e32 v189, v189
	v_exp_f32_e32 v190, v190
	v_exp_f32_e32 v191, v191
	v_pk_add_f32 v[188:189], v[188:189], 1.0 op_sel_hi:[1,0]
	v_pk_add_f32 v[190:191], v[190:191], 1.0 op_sel_hi:[1,0]
	v_rcp_f32_e32 v188, v188
	v_rcp_f32_e32 v189, v189
	v_rcp_f32_e32 v190, v190
	v_rcp_f32_e32 v191, v191
	v_pk_mul_f32 v[14:15], v[14:15], v[188:189]
	v_pk_mul_f32 v[16:17], v[16:17], v[190:191]
	v_pk_mul_f32 v[6:7], v[6:7], v[14:15]
	v_pk_mul_f32 v[8:9], v[8:9], v[16:17]
	v_cvt_pk_bf16_f32 v184, v6, v7
	v_cvt_pk_bf16_f32 v185, v8, v9
	v_pk_mul_f32 v[188:189], v[10:11], v[192:193] op_sel_hi:[1,0]
	v_pk_mul_f32 v[190:191], v[12:13], v[192:193] op_sel_hi:[1,0]
	v_exp_f32_e32 v188, v188
	v_exp_f32_e32 v189, v189
	v_exp_f32_e32 v190, v190
	v_exp_f32_e32 v191, v191
	v_pk_add_f32 v[188:189], v[188:189], 1.0 op_sel_hi:[1,0]
	v_pk_add_f32 v[190:191], v[190:191], 1.0 op_sel_hi:[1,0]
	v_rcp_f32_e32 v188, v188
	v_rcp_f32_e32 v189, v189
	v_rcp_f32_e32 v190, v190
	v_rcp_f32_e32 v191, v191
	v_pk_mul_f32 v[10:11], v[10:11], v[188:189]
	v_pk_mul_f32 v[12:13], v[12:13], v[190:191]
	v_pk_mul_f32 v[2:3], v[2:3], v[10:11]
	v_pk_mul_f32 v[4:5], v[4:5], v[12:13]
	v_cvt_pk_bf16_f32 v186, v2, v3
	v_cvt_pk_bf16_f32 v187, v4, v5
	v_lshl_add_u64 v[182:183], v[182:183], 0, v[176:177]
	global_store_dwordx4 v[182:183], v[184:187], off
	s_mov_b64 s[22:23], -1
	s_andn2_b64 vcc, exec, s[2:3]
	s_cbranch_vccnz .LBB0_1176
	s_andn2_b64 vcc, exec, s[6:7]
	s_cbranch_vccnz .LBB0_1175
	s_barrier
	s_branch .LBB0_1175
